# GEMM prologues (all 10): second K-tile's six LDS-DMA loads issued before the first wait (vmcnt(2) became vmcnt(8) after them)
# baseline (speedup 1.0000x reference)
; #define PG8_STAGE(bufoff, gbase, voff) do { _Pragma("unroll") for (int _i = 0; _i < 2; ++_i) \
;         __builtin_amdgcn_global_load_lds((const unsigned*)((const char*)(gbase) + (voff)[_i]), (PG8_LAS unsigned*)(lds + (bufoff) + ldsw + _i * 8192), 16, 0, 0); } while (0)
; #define PG8_WAIT_V(n) asm volatile("s_waitcnt vmcnt(" #n ")" ::: "memory")
; #define PG8_BAR __builtin_amdgcn_s_barrier()
; template <class Epi, class Sched, bool ALIGN_EPI = false, bool SP2 = false>
; __device__ __forceinline__ void gemm_phase(PG8_LAS unsigned char* lds, const Gemm g, const Sched& S, const Epi& E) {
;     ...
;     const int aoff = lds_byte(wr * 64 + fr, fq * 8), boff = lds_byte(wc * 32 + fr, fq * 8);
;     ...
;         PG8_STAGE(PG8_SB(0, 0), cB, voffB); PG8_STAGE(PG8_SB(0, 1), cB + hstepB, voffB); PG8_STAGE(PG8_SA(0, 0), cA, voffA); PG8_STAGE(PG8_SA(0, 1), cA + hstepA, voffA);
;         if (wr == 1) PG8_BAR;
;         PG8_WAIT_V(2); PG8_BAR;
;         PG8_STAGE(PG8_SB(1, 0), cB + kstep, voffB); PG8_STAGE(PG8_SA(1, 0), cA + kstep, voffA); PG8_STAGE(PG8_SB(1, 1), cB + hstepB + kstep, voffB);
;         PG8_WAIT_V(6); PG8_BAR;
.LBB0_140:
	v_readlane_b32 s48, v252, 52
	v_readlane_b32 s49, v252, 53
	v_mov_b32_e32 v151, v1
	v_readlane_b32 s46, v252, 48
	v_lshl_add_u64 v[10:11], s[48:49], 0, v[0:1]
	v_lshl_add_u64 v[12:13], s[48:49], 0, v[150:151]
	v_mov_b32_e32 v155, v1
	v_readlane_b32 s47, v252, 49
	s_add_i32 m0, s9, 0x18000
	v_lshl_add_u64 v[10:11], v[10:11], 0, s[2:3]
	v_lshl_add_u64 v[14:15], s[46:47], 0, v[154:155]
	v_mov_b32_e32 v153, v1
	global_load_lds_dwordx4 v[10:11], off
	v_lshl_add_u64 v[10:11], v[12:13], 0, s[2:3]
	s_add_i32 m0, s9, 0x1a000
	s_add_i32 s35, s9, 0x8000
	v_lshl_add_u64 v[16:17], s[46:47], 0, v[152:153]
	global_load_lds_dwordx4 v[10:11], off
	v_lshl_add_u64 v[10:11], v[14:15], 0, s[2:3]
	s_mov_b32 m0, s35
	s_add_i32 s52, s9, 0xa000
	v_readlane_b32 s20, v252, 54
	global_load_lds_dwordx4 v[10:11], off
	v_lshl_add_u64 v[10:11], v[16:17], 0, s[2:3]
	s_mov_b32 m0, s52
	v_readlane_b32 s21, v252, 55
	global_load_lds_dwordx4 v[10:11], off
	s_add_i32 m0, s9, 0x1c000
	v_lshl_add_u64 v[10:11], s[20:21], 0, v[0:1]
	global_load_lds_dwordx4 v[10:11], off
	v_lshl_add_u64 v[10:11], s[20:21], 0, v[150:151]
	s_add_i32 m0, s9, 0x1e000
	v_and_b32_e32 v9, 15, v3
	global_load_lds_dwordx4 v[10:11], off
	s_waitcnt vmcnt(8)
	s_barrier
	v_lshrrev_b32_e32 v10, 1, v3
	v_and_b32_e32 v10, 24, v10
	v_lshlrev_b32_e32 v11, 1, v10
	v_lshlrev_b32_e32 v3, 2, v3
	s_lshl_b32 s10, s10, 5
	v_lshl_or_b32 v160, s11, 6, v9
	v_lshl_or_b32 v9, v9, 6, v11
	s_lshl_b32 s11, s11, 13
	v_and_b32_e32 v3, 32, v3
	s_and_b32 s10, s10, 0x60
	v_bitop3_b32 v11, v9, s11, v3 bitop3:0xde
	s_lshl_b32 s11, s10, 7
	v_bitop3_b32 v161, v9, s11, v3 bitop3:0xde
	v_lshlrev_b32_e32 v3, 14, v7
	v_and_b32_e32 v3, 0xffff8000, v3
	v_lshl_add_u32 v3, v6, 11, v3
	v_and_b32_e32 v6, 1, v7
	v_lshl_or_b32 v3, v6, 6, v3
	v_lshl_add_u32 v156, v8, 1, v3
	v_lshlrev_b32_e32 v3, 14, v2
	v_and_b32_e32 v3, 0xffff8000, v3
	s_waitcnt vmcnt(6)
	v_lshl_add_u32 v3, v4, 11, v3
	v_and_b32_e32 v2, 1, v2
	s_cmpk_lt_u32 s4, 0x100
	v_or_b32_e32 v162, s10, v10
	v_lshl_or_b32 v2, v2, 6, v3
	v_readlane_b32 s10, v252, 42
	s_cselect_b64 s[20:21], -1, 0
	v_mov_b32_e32 v157, v1
	v_lshl_add_u32 v158, v5, 1, v2
	v_mov_b32_e32 v159, v1
	s_mov_b32 s53, 0
	v_add_u32_e32 v163, 0, v11
	v_readlane_b32 s55, v252, 41
	s_mov_b32 s56, s10
	s_barrier
	v_readlane_b32 s11, v252, 43
	s_branch .LBB0_143

; #define PG8_STAGE(bufoff, gbase, voff) do { _Pragma("unroll") for (int _i = 0; _i < 2; ++_i) \
;         __builtin_amdgcn_global_load_lds((const unsigned*)((const char*)(gbase) + (voff)[_i]), (PG8_LAS unsigned*)(lds + (bufoff) + ldsw + _i * 8192), 16, 0, 0); } while (0)
; #define PG8_WAIT_V(n) asm volatile("s_waitcnt vmcnt(" #n ")" ::: "memory")
; #define PG8_BAR __builtin_amdgcn_s_barrier()
; template <class Epi, class Sched, bool ALIGN_EPI = false, bool SP2 = false>
; __device__ __forceinline__ void gemm_phase(PG8_LAS unsigned char* lds, const Gemm g, const Sched& S, const Epi& E) {
;     ...
;     const int aoff = lds_byte(wr * 64 + fr, fq * 8), boff = lds_byte(wc * 32 + fr, fq * 8);
;     ...
;         PG8_STAGE(PG8_SB(0, 0), cB, voffB); PG8_STAGE(PG8_SB(0, 1), cB + hstepB, voffB); PG8_STAGE(PG8_SA(0, 0), cA, voffA); PG8_STAGE(PG8_SA(0, 1), cA + hstepA, voffA);
;         if (wr == 1) PG8_BAR;
;         PG8_WAIT_V(2); PG8_BAR;
;         PG8_STAGE(PG8_SB(1, 0), cB + kstep, voffB); PG8_STAGE(PG8_SA(1, 0), cA + kstep, voffA); PG8_STAGE(PG8_SB(1, 1), cB + hstepB + kstep, voffB);
;         PG8_WAIT_V(6); PG8_BAR;
.LBB0_158:
	v_lshrrev_b32_e32 v18, 1, v16
	v_and_b32_e32 v18, 24, v18
	v_and_b32_e32 v17, 15, v16
	v_lshlrev_b32_e32 v19, 1, v18
	v_lshlrev_b32_e32 v16, 2, v16
	v_lshl_or_b32 v160, s10, 6, v17
	v_lshl_or_b32 v17, v17, 6, v19
	s_lshl_b32 s10, s10, 13
	v_and_b32_e32 v16, 32, v16
	v_bitop3_b32 v19, v17, s10, v16 bitop3:0xde
	s_lshl_b32 s10, s21, 5
	s_and_b32 s36, s10, 0x60
	s_add_i32 m0, s9, 0x18000
	v_lshl_add_u64 v[8:9], v[8:9], 0, s[2:3]
	s_lshl_b32 s10, s36, 7
	global_load_lds_dwordx4 v[8:9], off
	v_lshl_add_u64 v[6:7], v[6:7], 0, s[2:3]
	s_add_i32 m0, s9, 0x1a000
	s_add_i32 s35, s9, 0x8000
	s_add_i32 s39, s9, 0xa000
	v_bitop3_b32 v161, v17, s10, v16 bitop3:0xde
	global_load_lds_dwordx4 v[6:7], off
	v_lshl_add_u64 v[2:3], v[2:3], 0, s[2:3]
	s_mov_b32 m0, s35
	s_add_u32 s10, s50, 0x40080
	global_load_lds_dwordx4 v[2:3], off
	v_lshl_add_u64 v[2:3], v[4:5], 0, s[2:3]
	s_mov_b32 m0, s39
	s_addc_u32 s11, s51, 0
	global_load_lds_dwordx4 v[2:3], off
	s_add_i32 m0, s9, 0x1c000
	v_lshl_add_u64 v[2:3], s[10:11], 0, v[0:1]
	global_load_lds_dwordx4 v[2:3], off
	v_lshl_add_u64 v[2:3], s[10:11], 0, v[154:155]
	s_add_i32 m0, s9, 0x1e000
	s_cmpk_lt_u32 s4, 0x100
	global_load_lds_dwordx4 v[2:3], off
	s_waitcnt vmcnt(8)
	s_barrier
	v_lshlrev_b32_e32 v2, 14, v10
	v_and_b32_e32 v2, 0xffff8000, v2
	v_lshl_add_u32 v2, v11, 11, v2
	v_and_b32_e32 v3, 1, v10
	v_lshl_or_b32 v2, v3, 6, v2
	v_lshl_add_u32 v156, v12, 1, v2
	v_lshlrev_b32_e32 v2, 14, v13
	v_and_b32_e32 v2, 0xffff8000, v2
	s_waitcnt vmcnt(6)
	v_lshl_add_u32 v2, v14, 11, v2
	v_and_b32_e32 v3, 1, v13
	v_lshl_or_b32 v2, v3, 6, v2
	s_sext_i32_i16 s56, s20
	s_cselect_b64 s[20:21], -1, 0
	v_or_b32_e32 v162, s36, v18
	v_mov_b32_e32 v157, v1
	v_lshl_add_u32 v158, v15, 1, v2
	v_mov_b32_e32 v159, v1
	s_mov_b32 s55, 0
	v_add_u32_e32 v163, 0, v19
	s_barrier
	s_branch .LBB0_161

; #define PG8_STAGE(bufoff, gbase, voff) do { _Pragma("unroll") for (int _i = 0; _i < 2; ++_i) \
;         __builtin_amdgcn_global_load_lds((const unsigned*)((const char*)(gbase) + (voff)[_i]), (PG8_LAS unsigned*)(lds + (bufoff) + ldsw + _i * 8192), 16, 0, 0); } while (0)
; #define PG8_WAIT_V(n) asm volatile("s_waitcnt vmcnt(" #n ")" ::: "memory")
; #define PG8_BAR __builtin_amdgcn_s_barrier()
; template <class Epi, class Sched, bool ALIGN_EPI = false, bool SP2 = false>
; __device__ __forceinline__ void gemm_phase(PG8_LAS unsigned char* lds, const Gemm g, const Sched& S, const Epi& E) {
;     ...
;     const int aoff = lds_byte(wr * 64 + fr, fq * 8), boff = lds_byte(wc * 32 + fr, fq * 8);
;     ...
;         PG8_STAGE(PG8_SB(0, 0), cB, voffB); PG8_STAGE(PG8_SB(0, 1), cB + hstepB, voffB); PG8_STAGE(PG8_SA(0, 0), cA, voffA); PG8_STAGE(PG8_SA(0, 1), cA + hstepA, voffA);
;         if (wr == 1) PG8_BAR;
;         PG8_WAIT_V(2); PG8_BAR;
;         PG8_STAGE(PG8_SB(1, 0), cB + kstep, voffB); PG8_STAGE(PG8_SA(1, 0), cA + kstep, voffA); PG8_STAGE(PG8_SB(1, 1), cB + hstepB + kstep, voffB);
;         PG8_WAIT_V(6); PG8_BAR;
.LBB0_372:
	v_lshrrev_b32_e32 v12, 1, v2
	v_and_b32_e32 v12, 24, v12
	v_readlane_b32 s48, v253, 16
	v_and_b32_e32 v3, 15, v2
	v_lshlrev_b32_e32 v13, 1, v12
	v_lshlrev_b32_e32 v2, 2, v2
	s_lshl_b32 s1, s1, 5
	v_readlane_b32 s49, v253, 17
	v_lshl_or_b32 v156, s4, 6, v3
	v_lshl_or_b32 v3, v3, 6, v13
	s_lshl_b32 s4, s4, 13
	v_and_b32_e32 v2, 32, v2
	s_and_b32 s1, s1, 0x60
	v_lshl_add_u64 v[4:5], s[48:49], 0, v[0:1]
	v_mov_b32_e32 v151, v1
	v_readlane_b32 s50, v253, 12
	v_bitop3_b32 v13, v3, s4, v2 bitop3:0xde
	s_lshl_b32 s4, s1, 7
	v_lshl_add_u64 v[6:7], s[48:49], 0, v[150:151]
	v_mov_b32_e32 v155, v1
	v_readlane_b32 s51, v253, 13
	v_bitop3_b32 v157, v3, s4, v2 bitop3:0xde
	s_add_i32 m0, s9, 0x18000
	v_lshl_add_u64 v[2:3], v[4:5], 0, s[2:3]
	v_lshl_add_u64 v[8:9], s[50:51], 0, v[154:155]
	v_mov_b32_e32 v153, v1
	global_load_lds_dwordx4 v[2:3], off
	v_lshl_add_u64 v[2:3], v[6:7], 0, s[2:3]
	s_add_i32 m0, s9, 0x1a000
	s_add_i32 s35, s9, 0x8000
	v_lshl_add_u64 v[10:11], s[50:51], 0, v[152:153]
	global_load_lds_dwordx4 v[2:3], off
	v_lshl_add_u64 v[2:3], v[8:9], 0, s[2:3]
	s_mov_b32 m0, s35
	s_add_i32 s68, s9, 0xa000
	v_readlane_b32 s10, v253, 18
	global_load_lds_dwordx4 v[2:3], off
	v_lshl_add_u64 v[2:3], v[10:11], 0, s[2:3]
	s_mov_b32 m0, s68
	v_readlane_b32 s11, v253, 19
	global_load_lds_dwordx4 v[2:3], off
	s_add_i32 m0, s9, 0x1c000
	v_lshl_add_u64 v[2:3], s[10:11], 0, v[0:1]
	global_load_lds_dwordx4 v[2:3], off
	v_lshl_add_u64 v[2:3], s[10:11], 0, v[150:151]
	s_add_i32 m0, s9, 0x1e000
	s_cmpk_lt_u32 s0, 0x100
	global_load_lds_dwordx4 v[2:3], off
	s_waitcnt vmcnt(8)
	s_barrier
	s_waitcnt vmcnt(6)
	s_cselect_b64 s[40:41], -1, 0
	v_or_b32_e32 v158, s1, v12
	s_mov_b32 s69, 0
	v_add_u32_e32 v159, 0, v13
	v_readlane_b32 s90, v253, 4
	v_readlane_b32 s91, v253, 9
	s_barrier
	s_waitcnt vmcnt(0)
	s_branch .LBB0_375

; #define PG8_STAGE(bufoff, gbase, voff) do { _Pragma("unroll") for (int _i = 0; _i < 2; ++_i) \
;         __builtin_amdgcn_global_load_lds((const unsigned*)((const char*)(gbase) + (voff)[_i]), (PG8_LAS unsigned*)(lds + (bufoff) + ldsw + _i * 8192), 16, 0, 0); } while (0)
; #define PG8_WAIT_V(n) asm volatile("s_waitcnt vmcnt(" #n ")" ::: "memory")
; #define PG8_BAR __builtin_amdgcn_s_barrier()
; template <class Epi, class Sched, bool ALIGN_EPI = false, bool SP2 = false>
; __device__ __forceinline__ void gemm_phase(PG8_LAS unsigned char* lds, const Gemm g, const Sched& S, const Epi& E) {
;     ...
;     const int aoff = lds_byte(wr * 64 + fr, fq * 8), boff = lds_byte(wc * 32 + fr, fq * 8);
;     ...
;         PG8_STAGE(PG8_SB(0, 0), cB, voffB); PG8_STAGE(PG8_SB(0, 1), cB + hstepB, voffB); PG8_STAGE(PG8_SA(0, 0), cA, voffA); PG8_STAGE(PG8_SA(0, 1), cA + hstepA, voffA);
;         if (wr == 1) PG8_BAR;
;         PG8_WAIT_V(2); PG8_BAR;
;         PG8_STAGE(PG8_SB(1, 0), cB + kstep, voffB); PG8_STAGE(PG8_SA(1, 0), cA + kstep, voffA); PG8_STAGE(PG8_SB(1, 1), cB + hstepB + kstep, voffB);
;         PG8_WAIT_V(6); PG8_BAR;
.LBB0_390:
	v_lshrrev_b32_e32 v12, 1, v2
	v_and_b32_e32 v12, 24, v12
	v_readlane_b32 s50, v253, 30
	v_and_b32_e32 v3, 15, v2
	v_lshlrev_b32_e32 v13, 1, v12
	v_lshlrev_b32_e32 v2, 2, v2
	s_lshl_b32 s1, s1, 5
	v_readlane_b32 s51, v253, 31
	v_lshl_or_b32 v156, s4, 6, v3
	v_lshl_or_b32 v3, v3, 6, v13
	s_lshl_b32 s4, s4, 13
	v_and_b32_e32 v2, 32, v2
	s_and_b32 s1, s1, 0x60
	v_lshl_add_u64 v[4:5], s[50:51], 0, v[0:1]
	v_mov_b32_e32 v151, v1
	v_readlane_b32 s52, v253, 26
	v_bitop3_b32 v13, v3, s4, v2 bitop3:0xde
	s_lshl_b32 s4, s1, 7
	v_lshl_add_u64 v[6:7], s[50:51], 0, v[150:151]
	v_mov_b32_e32 v155, v1
	v_readlane_b32 s53, v253, 27
	v_bitop3_b32 v157, v3, s4, v2 bitop3:0xde
	s_add_i32 m0, s9, 0x18000
	v_lshl_add_u64 v[2:3], v[4:5], 0, s[2:3]
	v_lshl_add_u64 v[8:9], s[52:53], 0, v[154:155]
	v_mov_b32_e32 v153, v1
	global_load_lds_dwordx4 v[2:3], off
	v_lshl_add_u64 v[2:3], v[6:7], 0, s[2:3]
	s_add_i32 m0, s9, 0x1a000
	s_add_i32 s35, s9, 0x8000
	v_lshl_add_u64 v[10:11], s[52:53], 0, v[152:153]
	global_load_lds_dwordx4 v[2:3], off
	v_lshl_add_u64 v[2:3], v[8:9], 0, s[2:3]
	s_mov_b32 m0, s35
	s_add_i32 s88, s9, 0xa000
	v_readlane_b32 s10, v253, 32
	global_load_lds_dwordx4 v[2:3], off
	v_lshl_add_u64 v[2:3], v[10:11], 0, s[2:3]
	s_mov_b32 m0, s88
	v_readlane_b32 s11, v253, 33
	global_load_lds_dwordx4 v[2:3], off
	s_add_i32 m0, s9, 0x1c000
	v_lshl_add_u64 v[2:3], s[10:11], 0, v[0:1]
	global_load_lds_dwordx4 v[2:3], off
	v_lshl_add_u64 v[2:3], s[10:11], 0, v[150:151]
	s_add_i32 m0, s9, 0x1e000
	s_cmpk_lt_u32 s0, 0x100
	global_load_lds_dwordx4 v[2:3], off
	s_waitcnt vmcnt(8)
	s_barrier
	s_waitcnt vmcnt(6)
	s_cselect_b64 s[42:43], -1, 0
	v_or_b32_e32 v158, s1, v12
	s_mov_b32 s90, 0
	v_add_u32_e32 v159, 0, v13
	v_readlane_b32 s94, v253, 20
	v_readlane_b32 s95, v253, 25
	s_barrier
	s_branch .LBB0_393

; #define PG8_STAGE(bufoff, gbase, voff) do { _Pragma("unroll") for (int _i = 0; _i < 2; ++_i) \
;         __builtin_amdgcn_global_load_lds((const unsigned*)((const char*)(gbase) + (voff)[_i]), (PG8_LAS unsigned*)(lds + (bufoff) + ldsw + _i * 8192), 16, 0, 0); } while (0)
; #define PG8_WAIT_V(n) asm volatile("s_waitcnt vmcnt(" #n ")" ::: "memory")
; #define PG8_BAR __builtin_amdgcn_s_barrier()
; template <class Epi, class Sched, bool ALIGN_EPI = false, bool SP2 = false>
; __device__ __forceinline__ void gemm_phase(PG8_LAS unsigned char* lds, const Gemm g, const Sched& S, const Epi& E) {
;     ...
;     const int aoff = lds_byte(wr * 64 + fr, fq * 8), boff = lds_byte(wc * 32 + fr, fq * 8);
;     ...
;         PG8_STAGE(PG8_SB(0, 0), cB, voffB); PG8_STAGE(PG8_SB(0, 1), cB + hstepB, voffB); PG8_STAGE(PG8_SA(0, 0), cA, voffA); PG8_STAGE(PG8_SA(0, 1), cA + hstepA, voffA);
;         if (wr == 1) PG8_BAR;
;         PG8_WAIT_V(2); PG8_BAR;
;         PG8_STAGE(PG8_SB(1, 0), cB + kstep, voffB); PG8_STAGE(PG8_SA(1, 0), cA + kstep, voffA); PG8_STAGE(PG8_SB(1, 1), cB + hstepB + kstep, voffB);
;         PG8_WAIT_V(6); PG8_BAR;
.LBB0_412:
	v_lshrrev_b32_e32 v12, 1, v2
	v_and_b32_e32 v12, 24, v12
	v_readlane_b32 s48, v253, 46
	v_and_b32_e32 v3, 15, v2
	v_lshlrev_b32_e32 v13, 1, v12
	v_lshlrev_b32_e32 v2, 2, v2
	s_lshl_b32 s1, s1, 5
	v_readlane_b32 s49, v253, 47
	v_lshl_or_b32 v156, s4, 6, v3
	v_lshl_or_b32 v3, v3, 6, v13
	s_lshl_b32 s4, s4, 13
	v_and_b32_e32 v2, 32, v2
	s_and_b32 s1, s1, 0x60
	v_lshl_add_u64 v[4:5], s[48:49], 0, v[0:1]
	v_mov_b32_e32 v151, v1
	v_readlane_b32 s50, v253, 42
	v_bitop3_b32 v13, v3, s4, v2 bitop3:0xde
	s_lshl_b32 s4, s1, 7
	v_lshl_add_u64 v[6:7], s[48:49], 0, v[150:151]
	v_mov_b32_e32 v155, v1
	v_readlane_b32 s51, v253, 43
	v_bitop3_b32 v157, v3, s4, v2 bitop3:0xde
	s_add_i32 m0, s9, 0x18000
	v_lshl_add_u64 v[2:3], v[4:5], 0, s[2:3]
	v_lshl_add_u64 v[8:9], s[50:51], 0, v[154:155]
	v_mov_b32_e32 v153, v1
	global_load_lds_dwordx4 v[2:3], off
	v_lshl_add_u64 v[2:3], v[6:7], 0, s[2:3]
	s_add_i32 m0, s9, 0x1a000
	s_add_i32 s35, s9, 0x8000
	v_lshl_add_u64 v[10:11], s[50:51], 0, v[152:153]
	global_load_lds_dwordx4 v[2:3], off
	v_lshl_add_u64 v[2:3], v[8:9], 0, s[2:3]
	s_mov_b32 m0, s35
	s_add_i32 s88, s9, 0xa000
	v_readlane_b32 s10, v253, 48
	global_load_lds_dwordx4 v[2:3], off
	v_lshl_add_u64 v[2:3], v[10:11], 0, s[2:3]
	s_mov_b32 m0, s88
	v_readlane_b32 s11, v253, 49
	global_load_lds_dwordx4 v[2:3], off
	s_add_i32 m0, s9, 0x1c000
	v_lshl_add_u64 v[2:3], s[10:11], 0, v[0:1]
	global_load_lds_dwordx4 v[2:3], off
	v_lshl_add_u64 v[2:3], s[10:11], 0, v[150:151]
	s_add_i32 m0, s9, 0x1e000
	s_cmpk_lt_u32 s0, 0x100
	global_load_lds_dwordx4 v[2:3], off
	s_waitcnt vmcnt(8)
	s_barrier
	s_waitcnt vmcnt(6)
	v_or_b32_e32 v158, s1, v12
	v_readlane_b32 s0, v253, 34
	s_cselect_b64 s[40:41], -1, 0
	s_mov_b32 s90, 0
	v_add_u32_e32 v159, 0, v13
	v_readlane_b32 s94, v254, 30
	s_mov_b32 s95, s0
	s_barrier
	v_readlane_b32 s1, v253, 35
	s_branch .LBB0_415

; #define PG8_STAGE(bufoff, gbase, voff) do { _Pragma("unroll") for (int _i = 0; _i < 2; ++_i) \
;         __builtin_amdgcn_global_load_lds((const unsigned*)((const char*)(gbase) + (voff)[_i]), (PG8_LAS unsigned*)(lds + (bufoff) + ldsw + _i * 8192), 16, 0, 0); } while (0)
; #define PG8_WAIT_V(n) asm volatile("s_waitcnt vmcnt(" #n ")" ::: "memory")
; #define PG8_BAR __builtin_amdgcn_s_barrier()
; template <class Epi, class Sched, bool ALIGN_EPI = false, bool SP2 = false>
; __device__ __forceinline__ void gemm_phase(PG8_LAS unsigned char* lds, const Gemm g, const Sched& S, const Epi& E) {
;     ...
;     for (int i = 0; i < 2; ++i) { int R, C; stage_rc(tid * 16 + i * 8192, R, C); const int Rb = Epi::PERM ? ((R & ~31) + perm32(R & 31)) : R;
;         voffA[i] = (unsigned)(R * g.lda + C) * 2u; voffB[i] = (unsigned)(Rb * g.ldb + C) * 2u; }
;     ...
;         PG8_STAGE(PG8_SB(0, 0), cB, voffB); PG8_STAGE(PG8_SB(0, 1), cB + hstepB, voffB); PG8_STAGE(PG8_SA(0, 0), cA, voffA); PG8_STAGE(PG8_SA(0, 1), cA + hstepA, voffA);
;         if (wr == 1) PG8_BAR;
;         PG8_WAIT_V(2); PG8_BAR;
;         PG8_STAGE(PG8_SB(1, 0), cB + kstep, voffB); PG8_STAGE(PG8_SA(1, 0), cA + kstep, voffA); PG8_STAGE(PG8_SB(1, 1), cB + hstepB + kstep, voffB);
;         PG8_WAIT_V(6); PG8_BAR;
.LBB0_593:
	v_lshl_add_u64 v[10:11], s[52:53], 0, v[0:1]
	v_mov_b32_e32 v151, v1
	v_readlane_b32 s50, v253, 52
	s_lshl_b32 s11, s11, 5
	v_lshl_add_u64 v[12:13], s[52:53], 0, v[150:151]
	v_mov_b32_e32 v155, v1
	v_readlane_b32 s51, v253, 53
	s_and_b32 s11, s11, 0x60
	s_add_i32 m0, s31, 0x18000
	v_lshl_add_u64 v[10:11], v[10:11], 0, s[2:3]
	v_lshl_add_u64 v[14:15], s[50:51], 0, v[154:155]
	v_mov_b32_e32 v153, v1
	s_lshl_b32 s12, s10, 13
	s_lshl_b32 s13, s11, 7
	global_load_lds_dwordx4 v[10:11], off
	v_lshl_add_u64 v[10:11], v[12:13], 0, s[2:3]
	s_add_i32 m0, s31, 0x1a000
	s_add_i32 s57, s31, 0x8000
	s_add_i32 s62, s31, 0xa000
	v_lshl_add_u64 v[16:17], s[50:51], 0, v[152:153]
	global_load_lds_dwordx4 v[10:11], off
	v_lshl_add_u64 v[10:11], v[14:15], 0, s[2:3]
	s_mov_b32 m0, s57
	s_add_u32 s38, s52, 0x40080
	global_load_lds_dwordx4 v[10:11], off
	v_lshl_add_u64 v[10:11], v[16:17], 0, s[2:3]
	s_mov_b32 m0, s62
	s_addc_u32 s39, s53, 0
	global_load_lds_dwordx4 v[10:11], off
	s_add_i32 m0, s31, 0x1c000
	v_lshl_add_u64 v[10:11], s[38:39], 0, v[0:1]
	global_load_lds_dwordx4 v[10:11], off
	v_lshl_add_u64 v[10:11], s[38:39], 0, v[150:151]
	s_add_i32 m0, s31, 0x1e000
	v_and_b32_e32 v9, 15, v2
	global_load_lds_dwordx4 v[10:11], off
	s_waitcnt vmcnt(8)
	s_barrier
	v_lshrrev_b32_e32 v10, 1, v2
	v_and_b32_e32 v10, 24, v10
	v_lshlrev_b32_e32 v11, 1, v10
	v_lshlrev_b32_e32 v2, 2, v2
	v_lshl_or_b32 v162, s10, 6, v9
	v_lshl_or_b32 v9, v9, 6, v11
	v_and_b32_e32 v2, 32, v2
	v_bitop3_b32 v11, v9, s12, v2 bitop3:0xde
	v_bitop3_b32 v163, v9, s13, v2 bitop3:0xde
	v_lshlrev_b32_e32 v2, 14, v7
	v_and_b32_e32 v2, 0xffff8000, v2
	v_lshl_add_u32 v2, v6, 11, v2
	v_and_b32_e32 v6, 1, v7
	v_lshl_or_b32 v2, v6, 6, v2
	v_lshl_add_u32 v156, v8, 1, v2
	v_lshlrev_b32_e32 v2, 14, v3
	v_and_b32_e32 v2, 0xffff8000, v2
	s_waitcnt vmcnt(6)
	v_lshl_add_u32 v2, v4, 11, v2
	v_and_b32_e32 v3, 1, v3
	s_cmpk_lt_u32 s4, 0x100
	v_or_b32_e32 v164, s11, v10
	v_lshl_or_b32 v2, v3, 6, v2
	v_readlane_b32 s10, v254, 23
	s_cselect_b64 s[40:41], -1, 0
	v_mov_b32_e32 v157, v1
	v_lshl_add_u32 v158, v5, 1, v2
	v_mov_b32_e32 v159, v1
	s_mov_b32 s63, 0
	v_add_u32_e32 v165, 0, v11
	s_mov_b32 s68, s59
	s_mov_b32 s69, s10
	s_barrier
	v_readlane_b32 s11, v254, 24
	s_waitcnt vmcnt(0)
	s_branch .LBB0_596

; #define PG8_STAGE(bufoff, gbase, voff) do { _Pragma("unroll") for (int _i = 0; _i < 2; ++_i) \
;         __builtin_amdgcn_global_load_lds((const unsigned*)((const char*)(gbase) + (voff)[_i]), (PG8_LAS unsigned*)(lds + (bufoff) + ldsw + _i * 8192), 16, 0, 0); } while (0)
; #define PG8_WAIT_V(n) asm volatile("s_waitcnt vmcnt(" #n ")" ::: "memory")
; #define PG8_BAR __builtin_amdgcn_s_barrier()
; template <class Epi, class Sched, bool ALIGN_EPI = false, bool SP2 = false>
; __device__ __forceinline__ void gemm_phase(PG8_LAS unsigned char* lds, const Gemm g, const Sched& S, const Epi& E) {
;     ...
;     for (int i = 0; i < 2; ++i) { int R, C; stage_rc(tid * 16 + i * 8192, R, C); const int Rb = Epi::PERM ? ((R & ~31) + perm32(R & 31)) : R;
;         voffA[i] = (unsigned)(R * g.lda + C) * 2u; voffB[i] = (unsigned)(Rb * g.ldb + C) * 2u; }
;     ...
;         PG8_STAGE(PG8_SB(0, 0), cB, voffB); PG8_STAGE(PG8_SB(0, 1), cB + hstepB, voffB); PG8_STAGE(PG8_SA(0, 0), cA, voffA); PG8_STAGE(PG8_SA(0, 1), cA + hstepA, voffA);
;         if (wr == 1) PG8_BAR;
;         PG8_WAIT_V(2); PG8_BAR;
;         PG8_STAGE(PG8_SB(1, 0), cB + kstep, voffB); PG8_STAGE(PG8_SA(1, 0), cA + kstep, voffA); PG8_STAGE(PG8_SB(1, 1), cB + hstepB + kstep, voffB);
;         PG8_WAIT_V(6); PG8_BAR;
.LBB0_613:
	v_lshrrev_b32_e32 v18, 1, v8
	v_and_b32_e32 v18, 24, v18
	s_lshl_b32 s8, s8, 5
	v_and_b32_e32 v9, 15, v8
	v_lshlrev_b32_e32 v19, 1, v18
	v_lshlrev_b32_e32 v8, 2, v8
	s_and_b32 s12, s8, 0x60
	v_lshl_add_u64 v[10:11], s[56:57], 0, v[0:1]
	v_mov_b32_e32 v151, v1
	v_lshl_or_b32 v168, s9, 6, v9
	v_lshl_or_b32 v9, v9, 6, v19
	s_lshl_b32 s9, s9, 13
	v_and_b32_e32 v8, 32, v8
	s_lshl_b32 s8, s12, 7
	v_lshl_add_u64 v[12:13], s[56:57], 0, v[150:151]
	v_mov_b32_e32 v155, v1
	v_bitop3_b32 v19, v9, s9, v8 bitop3:0xde
	v_bitop3_b32 v169, v9, s8, v8 bitop3:0xde
	s_add_i32 m0, s53, 0x18000
	v_lshl_add_u64 v[8:9], v[10:11], 0, s[2:3]
	v_lshl_add_u64 v[14:15], s[54:55], 0, v[154:155]
	v_mov_b32_e32 v153, v1
	global_load_lds_dwordx4 v[8:9], off
	v_lshl_add_u64 v[8:9], v[12:13], 0, s[2:3]
	s_add_i32 m0, s53, 0x1a000
	s_add_i32 s8, s53, 0x8000
	s_add_i32 s9, s53, 0xa000
	v_lshl_add_u64 v[16:17], s[54:55], 0, v[152:153]
	global_load_lds_dwordx4 v[8:9], off
	v_lshl_add_u64 v[8:9], v[14:15], 0, s[2:3]
	s_mov_b32 m0, s8
	s_add_u32 s10, s56, 0x20080
	global_load_lds_dwordx4 v[8:9], off
	v_lshl_add_u64 v[8:9], v[16:17], 0, s[2:3]
	s_mov_b32 m0, s9
	s_addc_u32 s11, s57, 0
	global_load_lds_dwordx4 v[8:9], off
	s_add_i32 m0, s53, 0x1c000
	v_lshl_add_u64 v[8:9], s[10:11], 0, v[0:1]
	global_load_lds_dwordx4 v[8:9], off
	v_lshl_add_u64 v[8:9], s[10:11], 0, v[150:151]
	s_add_i32 m0, s53, 0x1e000
	s_cmpk_lt_u32 s4, 0x100
	global_load_lds_dwordx4 v[8:9], off
	s_waitcnt vmcnt(8)
	s_barrier
	v_lshlrev_b32_e32 v8, 13, v6
	v_and_b32_e32 v8, 0xffffc000, v8
	v_lshl_add_u32 v5, v5, 10, v8
	v_and_b32_e32 v6, 1, v6
	v_lshl_or_b32 v5, v6, 6, v5
	v_lshl_add_u32 v156, v7, 1, v5
	v_lshlrev_b32_e32 v5, 13, v2
	v_and_b32_e32 v5, 0xffffc000, v5
	s_waitcnt vmcnt(6)
	v_lshl_add_u32 v3, v3, 10, v5
	v_and_b32_e32 v2, 1, v2
	v_lshl_or_b32 v2, v2, 6, v3
	s_cselect_b64 s[42:43], -1, 0
	v_or_b32_e32 v170, s12, v18
	v_mov_b32_e32 v157, v1
	v_lshl_add_u32 v158, v4, 1, v2
	v_mov_b32_e32 v159, v1
	s_mov_b32 s90, 0
	v_add_u32_e32 v171, 0, v19
	s_barrier
	s_branch .LBB0_616

; #define PG8_STAGE(bufoff, gbase, voff) do { _Pragma("unroll") for (int _i = 0; _i < 2; ++_i) \
;         __builtin_amdgcn_global_load_lds((const unsigned*)((const char*)(gbase) + (voff)[_i]), (PG8_LAS unsigned*)(lds + (bufoff) + ldsw + _i * 8192), 16, 0, 0); } while (0)
; #define PG8_WAIT_V(n) asm volatile("s_waitcnt vmcnt(" #n ")" ::: "memory")
; #define PG8_BAR __builtin_amdgcn_s_barrier()
; template <class Epi, class Sched, bool ALIGN_EPI = false, bool SP2 = false>
; __device__ __forceinline__ void gemm_phase(PG8_LAS unsigned char* lds, const Gemm g, const Sched& S, const Epi& E) {
;     ...
;     for (int i = 0; i < 2; ++i) { int R, C; stage_rc(tid * 16 + i * 8192, R, C); const int Rb = Epi::PERM ? ((R & ~31) + perm32(R & 31)) : R;
;         voffA[i] = (unsigned)(R * g.lda + C) * 2u; voffB[i] = (unsigned)(Rb * g.ldb + C) * 2u; }
;     ...
;         PG8_STAGE(PG8_SB(0, 0), cB, voffB); PG8_STAGE(PG8_SB(0, 1), cB + hstepB, voffB); PG8_STAGE(PG8_SA(0, 0), cA, voffA); PG8_STAGE(PG8_SA(0, 1), cA + hstepA, voffA);
;         if (wr == 1) PG8_BAR;
;         PG8_WAIT_V(2); PG8_BAR;
;         PG8_STAGE(PG8_SB(1, 0), cB + kstep, voffB); PG8_STAGE(PG8_SA(1, 0), cA + kstep, voffA); PG8_STAGE(PG8_SB(1, 1), cB + hstepB + kstep, voffB);
;         PG8_WAIT_V(6); PG8_BAR;
.LBB0_716:
	v_readlane_b32 s50, v254, 2
	v_readlane_b32 s51, v254, 3
	v_mov_b32_e32 v151, v1
	v_readlane_b32 s48, v253, 62
	v_lshl_add_u64 v[10:11], s[50:51], 0, v[0:1]
	v_lshl_add_u64 v[12:13], s[50:51], 0, v[150:151]
	v_mov_b32_e32 v155, v1
	v_readlane_b32 s49, v253, 63
	s_add_i32 m0, s9, 0x18000
	v_lshl_add_u64 v[10:11], v[10:11], 0, s[2:3]
	v_lshl_add_u64 v[14:15], s[48:49], 0, v[154:155]
	v_mov_b32_e32 v153, v1
	global_load_lds_dwordx4 v[10:11], off
	v_lshl_add_u64 v[10:11], v[12:13], 0, s[2:3]
	s_add_i32 m0, s9, 0x1a000
	s_add_i32 s35, s9, 0x8000
	v_lshl_add_u64 v[16:17], s[48:49], 0, v[152:153]
	global_load_lds_dwordx4 v[10:11], off
	v_lshl_add_u64 v[10:11], v[14:15], 0, s[2:3]
	s_mov_b32 m0, s35
	s_add_i32 s54, s9, 0xa000
	v_readlane_b32 s12, v254, 4
	global_load_lds_dwordx4 v[10:11], off
	v_lshl_add_u64 v[10:11], v[16:17], 0, s[2:3]
	s_mov_b32 m0, s54
	v_readlane_b32 s13, v254, 5
	global_load_lds_dwordx4 v[10:11], off
	s_add_i32 m0, s9, 0x1c000
	v_lshl_add_u64 v[10:11], s[12:13], 0, v[0:1]
	global_load_lds_dwordx4 v[10:11], off
	v_lshl_add_u64 v[10:11], s[12:13], 0, v[150:151]
	s_add_i32 m0, s9, 0x1e000
	v_and_b32_e32 v9, 15, v3
	global_load_lds_dwordx4 v[10:11], off
	s_waitcnt vmcnt(8)
	s_barrier
	v_lshrrev_b32_e32 v10, 1, v3
	v_and_b32_e32 v10, 24, v10
	v_lshlrev_b32_e32 v11, 1, v10
	v_lshlrev_b32_e32 v3, 2, v3
	s_lshl_b32 s10, s10, 5
	v_lshl_or_b32 v166, s11, 6, v9
	v_lshl_or_b32 v9, v9, 6, v11
	s_lshl_b32 s11, s11, 13
	v_and_b32_e32 v3, 32, v3
	s_and_b32 s10, s10, 0x60
	v_bitop3_b32 v11, v9, s11, v3 bitop3:0xde
	s_lshl_b32 s11, s10, 7
	v_bitop3_b32 v167, v9, s11, v3 bitop3:0xde
	v_lshlrev_b32_e32 v3, 14, v7
	v_and_b32_e32 v3, 0xffff8000, v3
	v_lshl_add_u32 v3, v6, 11, v3
	v_and_b32_e32 v6, 1, v7
	v_lshl_or_b32 v3, v6, 6, v3
	v_lshl_add_u32 v156, v8, 1, v3
	v_lshlrev_b32_e32 v3, 14, v2
	v_and_b32_e32 v3, 0xffff8000, v3
	s_waitcnt vmcnt(6)
	v_lshl_add_u32 v3, v4, 11, v3
	v_and_b32_e32 v2, 1, v2
	s_cmpk_lt_u32 s4, 0x100
	v_or_b32_e32 v168, s10, v10
	v_lshl_or_b32 v2, v2, 6, v3
	v_readlane_b32 s10, v254, 23
	s_cselect_b64 s[20:21], -1, 0
	v_mov_b32_e32 v157, v1
	v_lshl_add_u32 v158, v5, 1, v2
	v_mov_b32_e32 v159, v1
	s_mov_b32 s55, 0
	v_add_u32_e32 v169, 0, v11
	s_mov_b32 s56, s59
	s_mov_b32 s57, s10
	s_barrier
	v_readlane_b32 s11, v254, 24
	s_branch .LBB0_719

; #define PG8_STAGE(bufoff, gbase, voff) do { _Pragma("unroll") for (int _i = 0; _i < 2; ++_i) \
;         __builtin_amdgcn_global_load_lds((const unsigned*)((const char*)(gbase) + (voff)[_i]), (PG8_LAS unsigned*)(lds + (bufoff) + ldsw + _i * 8192), 16, 0, 0); } while (0)
; #define PG8_WAIT_V(n) asm volatile("s_waitcnt vmcnt(" #n ")" ::: "memory")
; #define PG8_BAR __builtin_amdgcn_s_barrier()
; template <class Epi, class Sched, bool ALIGN_EPI = false, bool SP2 = false>
; __device__ __forceinline__ void gemm_phase(PG8_LAS unsigned char* lds, const Gemm g, const Sched& S, const Epi& E) {
;     ...
;     for (int i = 0; i < 2; ++i) { int R, C; stage_rc(tid * 16 + i * 8192, R, C); const int Rb = Epi::PERM ? ((R & ~31) + perm32(R & 31)) : R;
;         voffA[i] = (unsigned)(R * g.lda + C) * 2u; voffB[i] = (unsigned)(Rb * g.ldb + C) * 2u; }
;     ...
;         PG8_STAGE(PG8_SB(0, 0), cB, voffB); PG8_STAGE(PG8_SB(0, 1), cB + hstepB, voffB); PG8_STAGE(PG8_SA(0, 0), cA, voffA); PG8_STAGE(PG8_SA(0, 1), cA + hstepA, voffA);
;         if (wr == 1) PG8_BAR;
;         PG8_WAIT_V(2); PG8_BAR;
;         PG8_STAGE(PG8_SB(1, 0), cB + kstep, voffB); PG8_STAGE(PG8_SA(1, 0), cA + kstep, voffA); PG8_STAGE(PG8_SB(1, 1), cB + hstepB + kstep, voffB);
;         PG8_WAIT_V(6); PG8_BAR;
.LBB0_846:
	v_readlane_b32 s50, v254, 19
	v_readlane_b32 s51, v254, 20
	v_mov_b32_e32 v151, v1
	v_readlane_b32 s48, v254, 15
	v_lshl_add_u64 v[10:11], s[50:51], 0, v[0:1]
	v_lshl_add_u64 v[12:13], s[50:51], 0, v[150:151]
	v_mov_b32_e32 v155, v1
	v_readlane_b32 s49, v254, 16
	s_add_i32 m0, s9, 0x18000
	v_lshl_add_u64 v[10:11], v[10:11], 0, s[2:3]
	v_lshl_add_u64 v[14:15], s[48:49], 0, v[154:155]
	v_mov_b32_e32 v153, v1
	global_load_lds_dwordx4 v[10:11], off
	v_lshl_add_u64 v[10:11], v[12:13], 0, s[2:3]
	s_add_i32 m0, s9, 0x1a000
	s_add_i32 s35, s9, 0x8000
	v_lshl_add_u64 v[16:17], s[48:49], 0, v[152:153]
	global_load_lds_dwordx4 v[10:11], off
	v_lshl_add_u64 v[10:11], v[14:15], 0, s[2:3]
	s_mov_b32 m0, s35
	s_add_i32 s54, s9, 0xa000
	v_readlane_b32 s12, v254, 21
	global_load_lds_dwordx4 v[10:11], off
	v_lshl_add_u64 v[10:11], v[16:17], 0, s[2:3]
	s_mov_b32 m0, s54
	v_readlane_b32 s13, v254, 22
	global_load_lds_dwordx4 v[10:11], off
	s_add_i32 m0, s9, 0x1c000
	v_lshl_add_u64 v[10:11], s[12:13], 0, v[0:1]
	global_load_lds_dwordx4 v[10:11], off
	v_lshl_add_u64 v[10:11], s[12:13], 0, v[150:151]
	s_add_i32 m0, s9, 0x1e000
	v_and_b32_e32 v9, 15, v3
	global_load_lds_dwordx4 v[10:11], off
	s_waitcnt vmcnt(8)
	s_barrier
	v_lshrrev_b32_e32 v10, 1, v3
	v_and_b32_e32 v10, 24, v10
	v_lshlrev_b32_e32 v11, 1, v10
	v_lshlrev_b32_e32 v3, 2, v3
	s_lshl_b32 s10, s10, 5
	v_lshl_or_b32 v160, s11, 6, v9
	v_lshl_or_b32 v9, v9, 6, v11
	s_lshl_b32 s11, s11, 13
	v_and_b32_e32 v3, 32, v3
	s_and_b32 s10, s10, 0x60
	v_bitop3_b32 v11, v9, s11, v3 bitop3:0xde
	s_lshl_b32 s11, s10, 7
	v_bitop3_b32 v161, v9, s11, v3 bitop3:0xde
	v_lshlrev_b32_e32 v3, 14, v7
	v_and_b32_e32 v3, 0xffff8000, v3
	v_lshl_add_u32 v3, v6, 11, v3
	v_and_b32_e32 v6, 1, v7
	v_lshl_or_b32 v3, v6, 6, v3
	v_lshl_add_u32 v156, v8, 1, v3
	v_lshlrev_b32_e32 v3, 14, v2
	v_and_b32_e32 v3, 0xffff8000, v3
	s_waitcnt vmcnt(6)
	v_lshl_add_u32 v3, v4, 11, v3
	v_and_b32_e32 v2, 1, v2
	s_cmpk_lt_u32 s4, 0x100
	v_or_b32_e32 v162, s10, v10
	v_lshl_or_b32 v2, v2, 6, v3
	v_readlane_b32 s10, v254, 9
	s_cselect_b64 s[20:21], -1, 0
	v_mov_b32_e32 v157, v1
	v_lshl_add_u32 v158, v5, 1, v2
	v_mov_b32_e32 v159, v1
	s_mov_b32 s55, 0
	v_add_u32_e32 v163, 0, v11
	v_readlane_b32 s56, v254, 8
	s_mov_b32 s57, s10
	s_barrier
	v_readlane_b32 s11, v254, 10
	s_branch .LBB0_849

; #define PG8_STAGE(bufoff, gbase, voff) do { _Pragma("unroll") for (int _i = 0; _i < 2; ++_i) \
;         __builtin_amdgcn_global_load_lds((const unsigned*)((const char*)(gbase) + (voff)[_i]), (PG8_LAS unsigned*)(lds + (bufoff) + ldsw + _i * 8192), 16, 0, 0); } while (0)
; #define PG8_WAIT_V(n) asm volatile("s_waitcnt vmcnt(" #n ")" ::: "memory")
; #define PG8_BAR __builtin_amdgcn_s_barrier()
; template <class Epi, class Sched, bool ALIGN_EPI = false, bool SP2 = false>
; __device__ __forceinline__ void gemm_phase(PG8_LAS unsigned char* lds, const Gemm g, const Sched& S, const Epi& E) {
;     ...
;     for (int i = 0; i < 2; ++i) { int R, C; stage_rc(tid * 16 + i * 8192, R, C); const int Rb = Epi::PERM ? ((R & ~31) + perm32(R & 31)) : R;
;         voffA[i] = (unsigned)(R * g.lda + C) * 2u; voffB[i] = (unsigned)(Rb * g.ldb + C) * 2u; }
;     ...
;         PG8_STAGE(PG8_SB(0, 0), cB, voffB); PG8_STAGE(PG8_SB(0, 1), cB + hstepB, voffB); PG8_STAGE(PG8_SA(0, 0), cA, voffA); PG8_STAGE(PG8_SA(0, 1), cA + hstepA, voffA);
;         if (wr == 1) PG8_BAR;
;         PG8_WAIT_V(2); PG8_BAR;
;         PG8_STAGE(PG8_SB(1, 0), cB + kstep, voffB); PG8_STAGE(PG8_SA(1, 0), cA + kstep, voffA); PG8_STAGE(PG8_SB(1, 1), cB + hstepB + kstep, voffB);
;         PG8_WAIT_V(6); PG8_BAR;
.LBB0_919:
	v_readlane_b32 s48, v254, 36
	v_readlane_b32 s49, v254, 37
	v_mov_b32_e32 v151, v1
	v_readlane_b32 s46, v254, 32
	v_lshl_add_u64 v[10:11], s[48:49], 0, v[0:1]
	v_lshl_add_u64 v[12:13], s[48:49], 0, v[150:151]
	v_mov_b32_e32 v155, v1
	v_readlane_b32 s47, v254, 33
	s_add_i32 m0, s9, 0x18000
	v_lshl_add_u64 v[10:11], v[10:11], 0, s[2:3]
	v_lshl_add_u64 v[14:15], s[46:47], 0, v[154:155]
	v_mov_b32_e32 v153, v1
	global_load_lds_dwordx4 v[10:11], off
	v_lshl_add_u64 v[10:11], v[12:13], 0, s[2:3]
	s_add_i32 m0, s9, 0x1a000
	s_add_i32 s35, s9, 0x8000
	v_lshl_add_u64 v[16:17], s[46:47], 0, v[152:153]
	global_load_lds_dwordx4 v[10:11], off
	v_lshl_add_u64 v[10:11], v[14:15], 0, s[2:3]
	s_mov_b32 m0, s35
	s_add_i32 s52, s9, 0xa000
	v_readlane_b32 s12, v254, 38
	global_load_lds_dwordx4 v[10:11], off
	v_lshl_add_u64 v[10:11], v[16:17], 0, s[2:3]
	s_mov_b32 m0, s52
	v_readlane_b32 s13, v254, 39
	global_load_lds_dwordx4 v[10:11], off
	s_add_i32 m0, s9, 0x1c000
	v_lshl_add_u64 v[10:11], s[12:13], 0, v[0:1]
	global_load_lds_dwordx4 v[10:11], off
	v_lshl_add_u64 v[10:11], s[12:13], 0, v[150:151]
	s_add_i32 m0, s9, 0x1e000
	v_and_b32_e32 v9, 15, v3
	global_load_lds_dwordx4 v[10:11], off
	s_waitcnt vmcnt(8)
	s_barrier
	v_lshrrev_b32_e32 v10, 1, v3
	v_and_b32_e32 v10, 24, v10
	v_lshlrev_b32_e32 v11, 1, v10
	v_lshlrev_b32_e32 v3, 2, v3
	s_lshl_b32 s10, s10, 5
	v_lshl_or_b32 v166, s11, 6, v9
	v_lshl_or_b32 v9, v9, 6, v11
	s_lshl_b32 s11, s11, 13
	v_and_b32_e32 v3, 32, v3
	s_and_b32 s10, s10, 0x60
	v_bitop3_b32 v11, v9, s11, v3 bitop3:0xde
	s_lshl_b32 s11, s10, 7
	v_bitop3_b32 v167, v9, s11, v3 bitop3:0xde
	v_lshlrev_b32_e32 v3, 16, v7
	v_and_b32_e32 v3, 0xfffe0000, v3
	v_lshl_add_u32 v3, v6, 13, v3
	v_and_b32_e32 v6, 1, v7
	v_lshl_or_b32 v3, v6, 6, v3
	v_lshl_add_u32 v156, v8, 1, v3
	v_lshlrev_b32_e32 v3, 16, v2
	v_and_b32_e32 v3, 0xfffe0000, v3
	s_waitcnt vmcnt(6)
	v_lshl_add_u32 v3, v4, 13, v3
	v_and_b32_e32 v2, 1, v2
	s_cmpk_lt_u32 s4, 0x100
	v_or_b32_e32 v168, s10, v10
	v_lshl_or_b32 v2, v2, 6, v3
	v_readlane_b32 s10, v254, 23
	s_cselect_b64 s[20:21], -1, 0
	v_mov_b32_e32 v157, v1
	v_lshl_add_u32 v158, v5, 1, v2
	v_mov_b32_e32 v159, v1
	s_mov_b32 s53, 0
	v_add_u32_e32 v169, 0, v11
	s_mov_b32 s54, s59
	s_mov_b32 s55, s10
	s_barrier
	v_readlane_b32 s11, v254, 24
	s_branch .LBB0_922
